# PP per-head norm reductions: lane^1/^2/^4/^8 butterfly steps done with DPP adds instead of ds_bpermute round trips
# speedup vs baseline: 1.0107x; 1.0013x over previous
.LBB0_1629:
	s_or_b64 exec, exec, s[6:7]
	v_ashrrev_i32_e32 v81, 31, v80
	v_cvt_pk_bf16_f32 v20, v20, v21
	v_cvt_pk_bf16_f32 v21, v22, v23
	v_lshlrev_b64 v[22:23], 9, v[80:81]
	v_lshlrev_b32_e32 v114, 16, v112
	v_and_b32_e32 v115, 0xffff0000, v112
	v_lshl_add_u64 v[22:23], v[46:47], 0, v[22:23]
	global_store_dwordx2 v[22:23], v[20:21], off
	v_pk_mul_f32 v[20:21], v[114:115], v[114:115]
	v_and_b32_e32 v112, 0xffff0000, v113
	v_lshlrev_b32_e32 v113, 16, v113
	v_add_f32_e32 v20, v20, v21
	v_xor_b32_e32 v21, 1, v226
	v_pk_mul_f32 v[22:23], v[112:113], v[112:113]
	v_cmp_lt_i32_e32 vcc, v21, v26
	v_add_f32_e32 v20, v23, v20
	v_add_f32_e32 v20, v22, v20
	v_cndmask_b32_e32 v21, v226, v21, vcc
	v_lshlrev_b32_e32 v21, 2, v21
	v_cmp_lt_i32_e32 vcc, v27, v26
	s_mov_b32 s6, 0x800000
	v_pk_mov_b32 v[116:117], v[112:113], v[112:113] op_sel:[1,0]
	s_waitcnt lgkmcnt(0)
	s_nop 1
	v_add_f32_dpp v22, v20, v20 quad_perm:[1,0,3,2] row_mask:0xf bank_mask:0xf
	v_cndmask_b32_e32 v20, v226, v27, vcc
	v_lshlrev_b32_e32 v20, 2, v20
	s_waitcnt lgkmcnt(0)
	s_nop 1
	v_add_f32_dpp v23, v22, v22 quad_perm:[2,3,0,1] row_mask:0xf bank_mask:0xf
	v_xor_b32_e32 v22, 4, v226
	v_cmp_lt_i32_e32 vcc, v22, v26
	s_nop 1
	v_cndmask_b32_e32 v22, v226, v22, vcc
	v_lshlrev_b32_e32 v22, 2, v22
	s_waitcnt lgkmcnt(0)
	s_nop 1
	v_add_f32_dpp v27, v23, v23 row_half_mirror row_mask:0xf bank_mask:0xf
	v_xor_b32_e32 v23, 8, v226
	v_cmp_lt_i32_e32 vcc, v23, v26
	s_nop 1
	v_cndmask_b32_e32 v23, v226, v23, vcc
	v_lshlrev_b32_e32 v23, 2, v23
	s_waitcnt lgkmcnt(0)
	s_nop 1
	v_add_f32_dpp v27, v27, v27 row_mirror row_mask:0xf bank_mask:0xf
	v_fmamk_f32 v27, v27, 0x3c800000, v225
	v_cmp_gt_f32_e32 vcc, s6, v27
	v_mul_f32_e32 v29, 0x4b800000, v27
	s_nop 0
	v_cndmask_b32_e32 v27, v27, v29, vcc
	v_rsq_f32_e32 v27, v27
	s_nop 0
	v_mul_f32_e32 v29, 0x45800000, v27
	v_cndmask_b32_e32 v112, v27, v29, vcc
	v_pk_mul_f32 v[114:115], v[112:113], v[114:115] op_sel_hi:[0,1]
	v_pk_mul_f32 v[112:113], v[112:113], v[116:117] op_sel_hi:[0,1]
	v_pk_mul_f32 v[18:19], v[18:19], v[112:113]
	v_pk_mul_f32 v[16:17], v[16:17], v[114:115]
	s_and_saveexec_b64 s[6:7], s[50:51]
	s_cbranch_execz .LBB0_1631
	ds_bpermute_b32 v27, v22, v16
	ds_bpermute_b32 v29, v22, v17
	v_mov_b32_e32 v116, v105
	v_mov_b32_e32 v117, v107
	v_mov_b32_e32 v118, v19
	s_waitcnt lgkmcnt(1)
	v_cndmask_b32_e64 v114, -v27, v27, s[46:47]
	ds_bpermute_b32 v27, v22, v18
	s_waitcnt lgkmcnt(1)
	v_cndmask_b32_e64 v115, -v29, v29, s[46:47]
	v_pk_mul_f32 v[114:115], v[116:117], v[114:115]
	v_mov_b32_e32 v112, v104
	v_mov_b32_e32 v113, v106
	s_waitcnt lgkmcnt(0)
	v_cndmask_b32_e64 v27, -v27, v27, s[46:47]
	v_mul_f32_e32 v116, v109, v27
	ds_bpermute_b32 v27, v22, v19
	v_mul_f32_e32 v18, v108, v18
	v_pk_fma_f32 v[16:17], v[112:113], v[16:17], v[114:115]
	s_waitcnt lgkmcnt(0)
	v_cndmask_b32_e64 v119, -v27, v27, s[46:47]
	v_pk_mul_f32 v[118:119], v[110:111], v[118:119]
	s_nop 0
	v_mov_b32_e32 v19, v118
	v_mov_b32_e32 v117, v119
	v_pk_add_f32 v[18:19], v[18:19], v[116:117]
.LBB0_1631:
	s_or_b64 exec, exec, s[6:7]
	s_mov_b32 s6, 0x3e38aa3b
	v_pk_mul_f32 v[18:19], v[18:19], s[6:7] op_sel_hi:[1,0]
	v_pk_mul_f32 v[16:17], v[16:17], s[6:7] op_sel_hi:[1,0]
	s_mov_b32 s6, 0xb353000
	v_cvt_pk_bf16_f32 v16, v16, v17
	v_cvt_pk_bf16_f32 v17, v18, v19
	v_add_co_u32_e32 v18, vcc, s6, v24
	s_mov_b32 s6, 0x800000
	s_nop 0
	v_addc_co_u32_e32 v19, vcc, 0, v25, vcc
	global_store_dwordx2 v[18:19], v[16:17], off offset:1792
	v_pk_mul_f32 v[18:19], v[100:101], v[100:101]
	v_pk_mul_f32 v[16:17], v[102:103], v[102:103]
	v_add_f32_e32 v18, v18, v19
	v_add_f32_e32 v16, v16, v18
	v_add_f32_e32 v16, v17, v16
	s_waitcnt lgkmcnt(0)
	s_nop 1
	v_add_f32_dpp v16, v16, v16 quad_perm:[1,0,3,2] row_mask:0xf bank_mask:0xf
	s_waitcnt lgkmcnt(0)
	s_nop 1
	v_add_f32_dpp v16, v16, v16 quad_perm:[2,3,0,1] row_mask:0xf bank_mask:0xf
	s_waitcnt lgkmcnt(0)
	s_nop 1
	v_add_f32_dpp v16, v16, v16 row_half_mirror row_mask:0xf bank_mask:0xf
	s_waitcnt lgkmcnt(0)
	s_nop 1
	v_add_f32_dpp v16, v16, v16 row_mirror row_mask:0xf bank_mask:0xf
	v_fmamk_f32 v16, v16, 0x3c800000, v225
	v_cmp_gt_f32_e32 vcc, s6, v16
	v_mul_f32_e32 v17, 0x4b800000, v16
	s_nop 0
	v_cndmask_b32_e32 v16, v16, v17, vcc
	v_rsq_f32_e32 v16, v16
	s_nop 0
	v_mul_f32_e32 v17, 0x45800000, v16
	v_cndmask_b32_e32 v16, v16, v17, vcc
	v_pk_mul_f32 v[18:19], v[100:101], v[16:17] op_sel_hi:[1,0]
	v_pk_mul_f32 v[16:17], v[102:103], v[16:17] op_sel_hi:[1,0]
	v_pk_mul_f32 v[12:13], v[12:13], v[18:19]
	v_pk_mul_f32 v[14:15], v[14:15], v[16:17]
	s_mov_b64 vcc, 0
	s_and_saveexec_b64 s[6:7], s[52:53]
	s_xor_b64 s[6:7], exec, s[6:7]
	s_cbranch_execz .LBB0_1636
	s_and_saveexec_b64 s[8:9], s[0:1]
	s_cbranch_execz .LBB0_1634
	v_lshlrev_b64 v[16:17], 9, v[98:99]
	s_mov_b64 vcc, exec
	v_lshl_add_u64 v[16:17], v[68:69], 0, v[16:17]
	global_store_dwordx4 v[16:17], v[12:15], off

.LBB0_1640:
	s_or_b64 exec, exec, s[6:7]
	v_mul_f32_e32 v13, v89, v89
	v_xor_b32_e32 v12, 32, v226
	v_fmac_f32_e32 v13, v88, v88
	v_cmp_lt_i32_e32 vcc, v12, v26
	v_fmac_f32_e32 v13, v90, v90
	v_fmac_f32_e32 v13, v91, v91
	v_cndmask_b32_e32 v12, v226, v12, vcc
	v_lshlrev_b32_e32 v12, 2, v12
	ds_bpermute_b32 v14, v12, v13
	s_waitcnt lgkmcnt(0)
	v_add_f32_e32 v14, v13, v14
	v_xor_b32_e32 v13, 16, v226
	v_cmp_lt_i32_e32 vcc, v13, v26
	s_nop 1
	v_cndmask_b32_e32 v13, v226, v13, vcc
	v_lshlrev_b32_e32 v13, 2, v13
	ds_bpermute_b32 v15, v13, v14
	s_waitcnt lgkmcnt(0)
	v_add_f32_e32 v14, v14, v15
	s_waitcnt lgkmcnt(0)
	s_nop 1
	v_add_f32_dpp v14, v14, v14 row_mirror row_mask:0xf bank_mask:0xf
	s_waitcnt lgkmcnt(0)
	s_nop 1
	v_add_f32_dpp v14, v14, v14 row_half_mirror row_mask:0xf bank_mask:0xf
	s_waitcnt lgkmcnt(0)
	s_nop 1
	v_add_f32_dpp v14, v14, v14 quad_perm:[2,3,0,1] row_mask:0xf bank_mask:0xf
	ds_bpermute_b32 v15, v21, v14
	s_and_saveexec_b64 s[6:7], s[38:39]
	s_cbranch_execz .LBB0_1642
	s_waitcnt lgkmcnt(0)
	v_add_f32_e32 v14, v14, v15
	v_fmamk_f32 v14, v14, 0x3baaaaab, v225
	s_mov_b32 s8, 0x800000
	v_mul_f32_e32 v15, 0x4b800000, v14
	v_cmp_gt_f32_e32 vcc, s8, v14
	s_nop 1
	v_cndmask_b32_e32 v14, v14, v15, vcc
	v_rsq_f32_e32 v14, v14
	s_nop 0
	v_mul_f32_e32 v15, 0x45800000, v14
	v_cndmask_b32_e32 v14, v14, v15, vcc
	v_pk_mul_f32 v[16:17], v[88:89], v[14:15] op_sel_hi:[1,0]
	v_pk_mul_f32 v[14:15], v[90:91], v[14:15] op_sel_hi:[1,0]
	v_pk_mul_f32 v[8:9], v[8:9], v[16:17]
	v_pk_mul_f32 v[10:11], v[10:11], v[14:15]
	v_cvt_pk_bf16_f32 v8, v8, v9
	v_cvt_pk_bf16_f32 v9, v10, v11
	v_lshl_add_u64 v[10:11], v[72:73], 0, v[44:45]
	global_store_dwordx2 v[10:11], v[8:9], off
.LBB0_1642:
	s_or_b64 exec, exec, s[6:7]
	v_pk_mul_f32 v[10:11], v[82:83], v[82:83]
	v_pk_mul_f32 v[8:9], v[84:85], v[84:85]
	v_add_f32_e32 v10, v10, v11
	v_add_f32_e32 v8, v8, v10
	v_add_f32_e32 v8, v9, v8
	ds_bpermute_b32 v9, v12, v8
	s_waitcnt lgkmcnt(0)
	v_add_f32_e32 v8, v8, v9
	ds_bpermute_b32 v9, v13, v8
	s_waitcnt lgkmcnt(0)
	v_add_f32_e32 v8, v8, v9
	s_waitcnt lgkmcnt(0)
	s_nop 1
	v_add_f32_dpp v8, v8, v8 row_mirror row_mask:0xf bank_mask:0xf
	s_waitcnt lgkmcnt(0)
	s_nop 1
	v_add_f32_dpp v8, v8, v8 row_half_mirror row_mask:0xf bank_mask:0xf
	s_waitcnt lgkmcnt(0)
	s_nop 1
	v_add_f32_dpp v8, v8, v8 quad_perm:[2,3,0,1] row_mask:0xf bank_mask:0xf
	ds_bpermute_b32 v9, v21, v8
	s_and_saveexec_b64 s[6:7], s[0:1]
	s_cbranch_execz .LBB0_1646
	s_waitcnt lgkmcnt(0)
	v_add_f32_e32 v8, v8, v9
	v_fmamk_f32 v8, v8, 0x3c000000, v225
	s_mov_b32 s8, 0x800000
	v_mul_f32_e32 v9, 0x4b800000, v8
	v_cmp_gt_f32_e32 vcc, s8, v8
	s_nop 1
	v_cndmask_b32_e32 v8, v8, v9, vcc
	v_rsq_f32_e32 v8, v8
	s_nop 0
	v_mul_f32_e32 v9, 0x45800000, v8
	v_cndmask_b32_e32 v8, v8, v9, vcc
	v_pk_mul_f32 v[10:11], v[82:83], v[8:9] op_sel_hi:[1,0]
	v_pk_mul_f32 v[8:9], v[84:85], v[8:9] op_sel_hi:[1,0]
	v_pk_mul_f32 v[4:5], v[4:5], v[10:11]
	v_pk_mul_f32 v[6:7], v[6:7], v[8:9]
	s_and_saveexec_b64 s[8:9], s[52:53]
	s_cbranch_execz .LBB0_1645
	v_lshlrev_b64 v[8:9], 9, v[98:99]
	v_lshl_add_u64 v[8:9], v[70:71], 0, v[8:9]
	global_store_dwordx4 v[8:9], v[4:7], off
